# input prefetch under the grid-barrier wait: queue-first workgroups warm their sample item's K/V window-cache slices in L2 while waiting at the in-proj barrier (static item index)
# baseline (speedup 1.0000x reference)
; #define LAS __attribute__((address_space(3)))
; __device__ __forceinline__ void attn_sample_item(const Args& a, int l, int n, LAS unsigned char* lds, int tid, int lane, int wave) {
;     ...
;     const float* ck = a.in[5] + (size_t)(l * NSB + n) * 128 * 128; const float* cv = a.in[6] + (size_t)(l * NSB + n) * 128 * 128;
;     float* oks = a.out + O_KS + (size_t)(l * NSB + n) * 128 * 128; float* ovs = a.out + O_VS + (size_t)(l * NSB + n) * 128 * 128;
;     const int c16 = tid & 15, kvh = c16 >> 3, sub = c16 & 7;
;     u32x4 qws[4], zws[4];
;     if (wave < 2) attn_prefetch<true>(proj, MP + n * LS, wave * 4, lane, qws, zws);
;     f32x4 kc[4][2], vc[4][2];
; #pragma unroll
;     for (int pass = 0; pass < 4; ++pass) {
;         const int r = pass * 32 + (tid >> 4);
;         kc[pass][0] = __builtin_nontemporal_load((const f32x4*)(ck + r * 128 + c16 * 8)); kc[pass][1] = __builtin_nontemporal_load((const f32x4*)(ck + r * 128 + c16 * 8 + 4));
;         vc[pass][0] = __builtin_nontemporal_load((const f32x4*)(cv + r * 128 + c16 * 8)); vc[pass][1] = __builtin_nontemporal_load((const f32x4*)(cv + r * 128 + c16 * 8 + 4));
; __device__ __forceinline__ void p_mixer(const Args& a, int l, LAS unsigned char* lds, int tid, int lane, int wave, int bid, int G) {
;     constexpr int N_AP = NPB * 32 * 2, N_AS = NSB, N_CV = M / 64;
;     unsigned* head = (unsigned*)(a.ws + WS_BAR) + QUEUE_WORD + 64 * l;
;     volatile LAS unsigned* slot = (volatile LAS unsigned*)(lds + 131072 + 128);
;     const bool qfirst = ((bid >> 3) & 1) != 0;
;     bool prompt_done = false, queue_empty = false; int pulled = 0;
.LBB0_439:
	s_or_b64 exec, exec, s[0:1]
	s_cmp_lg_u32 s42, 0x100
	s_cbranch_scc1 .Lkvpf_skip
	s_bitcmp1_b32 s71, 3
	s_cbranch_scc0 .Lkvpf_skip
	v_readfirstlane_b32 s2, v208
	s_lshr_b32 s2, s2, 6
	s_cmp_eq_u32 s2, 0
	s_cbranch_scc1 .Lkvpf_skip
	s_lshr_b32 s3, s71, 4
	s_lshl_b32 s3, s3, 3
	s_and_b32 s4, s71, 7
	s_or_b32 s3, s3, s4
	s_lshl_b32 s4, s66, 7
	s_add_i32 s3, s3, s4
	s_lshl_b32 s3, s3, 16
	v_readlane_b32 s6, v253, 14
	v_readlane_b32 s7, v253, 15
	v_readlane_b32 s8, v253, 16
	v_readlane_b32 s9, v253, 17
	s_cmp_lt_u32 s2, 5
	s_cselect_b32 s6, s6, s8
	s_cselect_b32 s7, s7, s9
	s_cselect_b32 s4, 64, 0x140
	s_movk_i32 s5, 0xc0
	s_cselect_b32 s5, 0x100, s5
	s_add_u32 s6, s6, s3
	s_addc_u32 s7, s7, 0
	v_subrev_u32_e32 v228, s4, v208
	v_lshlrev_b32_e32 v229, 7, v228
	global_load_dword v227, v229, s[6:7]
	v_add_u32_e32 v228, s5, v228
	v_min_u32_e32 v228, 0x1ff, v228
	v_lshlrev_b32_e32 v229, 7, v228
	global_load_dword v227, v229, s[6:7]
	v_add_u32_e32 v228, s5, v228
	v_min_u32_e32 v228, 0x1ff, v228
	v_lshlrev_b32_e32 v229, 7, v228
	global_load_dword v227, v229, s[6:7]
.Lkvpf_skip:
	v_mov_b32_e32 v130, v208
	s_waitcnt lgkmcnt(0)
	s_barrier
	s_lshl_b32 s86, s66, 6
	v_readfirstlane_b32 s2, v130
	s_ashr_i32 s6, s2, 6
	s_lshl_b64 s[0:1], s[86:87], 2
	v_readlane_b32 s3, v254, 8
	s_add_u32 s4, s3, s0
	v_readlane_b32 s3, v254, 9
	s_addc_u32 s5, s3, s1
	v_writelane_b32 v255, s4, 15
	s_ashr_i32 s45, s2, 7
	s_lshl_b32 s2, s6, 1
	v_writelane_b32 v255, s5, 16
	s_and_b32 s2, s2, 2
	s_lshl_b32 s4, s6, 12
	s_add_i32 s7, s4, 0
	s_mul_i32 s4, s2, 0x1200
	s_lshl_b32 s33, s2, 5
	s_add_i32 s85, s4, 0
	s_mul_i32 s4, s2, 0xfffff600
	s_sub_i32 s61, 4, s2
	s_xor_b32 s83, s2, 3
	s_lshl_b32 s2, s6, 3
	s_lshl_b32 s10, s6, 8
	s_addk_i32 s2, 0xe000
	s_add_i32 s8, s10, 0
	v_writelane_b32 v255, s2, 17
	s_lshl_b32 s2, s66, 8
	s_add_i32 s60, s85, s4
	s_or_b32 s4, s33, 32
	v_writelane_b32 v255, s2, 18
	s_add_i32 s2, s8, 0x18000
	s_mul_i32 s5, s4, 0x90
	v_writelane_b32 v255, s2, 19
	s_add_i32 s2, s7, 0x19000
	s_add_i32 s82, s5, 0
	s_mulk_i32 s4, 0xffb0
	v_writelane_b32 v255, s2, 20
	s_lshl_b32 s72, s66, 2
	s_add_i32 s64, s7, 0x12000
	s_add_i32 s65, s8, 0x11000
	s_lshl_b32 s86, s66, 3
	s_add_i32 s70, s82, s4
	s_mul_i32 s4, s66, 0x600
	v_writelane_b32 v255, s66, 21
	s_lshl_b32 s2, s66, 7
	s_cmp_lt_i32 s6, 2
	v_writelane_b32 v255, s67, 22
	v_writelane_b32 v255, s2, 23
	s_cselect_b64 s[2:3], -1, 0
	v_writelane_b32 v255, s2, 24
	s_ashr_i32 s11, s10, 31
	s_mov_b32 s5, s87
	v_writelane_b32 v255, s3, 25
	v_writelane_b32 v255, s10, 26
	s_mul_i32 s2, s6, 0x5a00
	s_add_i32 s3, s2, 0
	v_writelane_b32 v255, s11, 27
	v_readlane_b32 s8, v253, 20
	s_mul_i32 s2, s6, 0xfffff600
	v_readlane_b32 s10, v253, 22
	v_readlane_b32 s11, v253, 23
	v_readlane_b32 s12, v253, 24
	v_readlane_b32 s13, v253, 25
	v_readlane_b32 s14, v253, 26
	v_readlane_b32 s15, v253, 27
	v_readlane_b32 s16, v253, 28
	v_readlane_b32 s17, v253, 29
	v_writelane_b32 v255, s3, 28
	s_add_i32 s2, s3, s2
	v_readlane_b32 s18, v253, 30
	v_readlane_b32 s19, v253, 31
	v_readlane_b32 s20, v253, 32
	v_readlane_b32 s21, v253, 33
	s_mov_b64 s[10:11], s[14:15]
	s_mov_b64 s[12:13], s[16:17]
	v_writelane_b32 v255, s2, 29
	s_lshl_b32 s2, s6, 2
	s_mov_b64 s[14:15], s[18:19]
	s_add_u32 s98, s14, s0
	s_mov_b64 s[16:17], s[20:21]
	s_addc_u32 s99, s15, s1
	s_lshl_b64 s[6:7], s[86:87], 2
	s_add_u32 s80, s16, s6
	s_addc_u32 s81, s17, s7
	s_add_u32 s62, s12, s0
	s_addc_u32 s63, s13, s1
	s_lshl_b64 s[0:1], s[4:5], 2
	s_add_u32 s0, s10, s0
	v_writelane_b32 v255, s2, 30
	s_addc_u32 s1, s11, s1
	v_writelane_b32 v255, s0, 31
	s_mov_b32 s93, 0
	s_mov_b64 s[68:69], 0
	v_writelane_b32 v255, s1, 32
	s_mov_b64 s[66:67], 0
	v_readlane_b32 s9, v253, 21
	v_readlane_b32 s22, v253, 34
	v_readlane_b32 s23, v253, 35
	s_branch .LBB0_441
